# selected loop: MFMA-first step head (the first two QK MFMAs issue before any exp)
# speedup vs baseline: 1.0064x; 1.0064x over previous
.Lsel_nodiag_0b:
	v_add_u32_e32 v187, s81, v208
	ds_read_b128 v[124:127], v187 offset:9216
	ds_read_b128 v[144:147], v187 offset:13824
	ds_read_b128 v[148:151], v187 offset:9248
	s_waitcnt lgkmcnt(6)
	v_mfma_f32_32x32x16_bf16 v[238:253], v[108:111], v[128:131], v[2:17]
	ds_read_b128 v[108:111], v0 offset:64
	s_waitcnt lgkmcnt(6)
	v_mfma_f32_32x32x16_bf16 v[222:237], v[112:115], v[128:131], v[2:17]
	ds_read_b128 v[112:115], v0 offset:4672
	v_exp_f32_e32 v80, v80
	v_exp_f32_e32 v81, v81
	v_exp_f32_e32 v82, v82
	v_exp_f32_e32 v83, v83
	v_exp_f32_e32 v84, v84
	v_exp_f32_e32 v85, v85
	v_exp_f32_e32 v86, v86
	v_exp_f32_e32 v87, v87
	v_add_f32_e32 v164, 0, v80
	v_add_f32_e32 v165, 0, v81
	v_add_f32_e32 v164, v82, v164
	v_add_f32_e32 v165, v83, v165
	v_cvt_pk_bf16_f32 v80, v80, v81
	v_cvt_pk_bf16_f32 v81, v82, v83
	v_add_f32_e32 v164, v84, v164
	v_add_f32_e32 v165, v85, v165
	v_add_f32_e32 v164, v86, v164
	v_add_f32_e32 v165, v87, v165
	v_cvt_pk_bf16_f32 v82, v84, v85
	v_cvt_pk_bf16_f32 v83, v86, v87
	v_cndmask_b32_e64 v80, v80, 0, s[72:73]
	v_cndmask_b32_e64 v81, v81, 0, s[72:73]
	v_cndmask_b32_e64 v82, v82, 0, s[72:73]
	v_cndmask_b32_e64 v83, v83, 0, s[72:73]
	v_exp_f32_e32 v88, v88
	v_exp_f32_e32 v89, v89
	s_waitcnt lgkmcnt(4)
	v_mfma_f32_32x32x16_bf16 v[48:63], v[124:127], v[80:83], v[48:63]
	ds_read_b128 v[124:127], v187 offset:13856
	v_exp_f32_e32 v90, v90
	v_exp_f32_e32 v91, v91
	s_waitcnt lgkmcnt(4)
	v_mfma_f32_32x32x16_bf16 v[32:47], v[144:147], v[80:83], v[32:47]
	ds_read_b128 v[144:147], v187 offset:9280
	v_exp_f32_e32 v92, v92
	v_exp_f32_e32 v93, v93
	v_mfma_f32_32x32x16_bf16 v[238:253], v[116:119], v[132:135], v[238:253]
	ds_read_b128 v[116:119], v0 offset:96
	v_exp_f32_e32 v94, v94
	v_exp_f32_e32 v95, v95
	v_mfma_f32_32x32x16_bf16 v[222:237], v[120:123], v[132:135], v[222:237]
	ds_read_b128 v[120:123], v0 offset:4704
	v_add_f32_e32 v164, v88, v164
	v_add_f32_e32 v165, v89, v165
	v_add_f32_e32 v164, v90, v164
	v_add_f32_e32 v165, v91, v165
	v_cvt_pk_bf16_f32 v88, v88, v89
	v_cvt_pk_bf16_f32 v89, v90, v91
	v_add_f32_e32 v164, v92, v164
	v_add_f32_e32 v165, v93, v165
	v_add_f32_e32 v164, v94, v164
	v_add_f32_e32 v165, v95, v165
	v_cvt_pk_bf16_f32 v90, v92, v93
	v_cvt_pk_bf16_f32 v91, v94, v95
	v_cndmask_b32_e64 v88, v88, 0, s[72:73]
	v_cndmask_b32_e64 v89, v89, 0, s[72:73]
	v_cndmask_b32_e64 v90, v90, 0, s[72:73]
	v_cndmask_b32_e64 v91, v91, 0, s[72:73]
	v_exp_f32_e32 v64, v64
	v_exp_f32_e32 v65, v65
	s_waitcnt lgkmcnt(6)
	v_mfma_f32_32x32x16_bf16 v[48:63], v[148:151], v[88:91], v[48:63]
	ds_read_b128 v[148:151], v187 offset:13888
	v_exp_f32_e32 v66, v66
	v_exp_f32_e32 v67, v67
	s_waitcnt lgkmcnt(4)
	v_mfma_f32_32x32x16_bf16 v[32:47], v[124:127], v[88:91], v[32:47]
	ds_read_b128 v[124:127], v187 offset:9312
	v_exp_f32_e32 v68, v68
	v_exp_f32_e32 v69, v69
	v_mfma_f32_32x32x16_bf16 v[238:253], v[108:111], v[136:139], v[238:253]
	v_exp_f32_e32 v70, v70
	v_exp_f32_e32 v71, v71
	v_mfma_f32_32x32x16_bf16 v[222:237], v[112:115], v[136:139], v[222:237]
	v_add_f32_e32 v164, v64, v164
	v_add_f32_e32 v165, v65, v165
	v_add_f32_e32 v164, v66, v164
	v_add_f32_e32 v165, v67, v165
	v_cvt_pk_bf16_f32 v64, v64, v65
	v_cvt_pk_bf16_f32 v65, v66, v67
	v_add_f32_e32 v164, v68, v164
	v_add_f32_e32 v165, v69, v165
	v_add_f32_e32 v164, v70, v164
	v_add_f32_e32 v165, v71, v165
	v_cvt_pk_bf16_f32 v66, v68, v69
	v_cvt_pk_bf16_f32 v67, v70, v71
	v_cndmask_b32_e64 v64, v64, 0, s[72:73]
	v_cndmask_b32_e64 v65, v65, 0, s[72:73]
	v_cndmask_b32_e64 v66, v66, 0, s[72:73]
	v_cndmask_b32_e64 v67, v67, 0, s[72:73]
	v_exp_f32_e32 v72, v72
	v_exp_f32_e32 v73, v73
	s_waitcnt lgkmcnt(4)
	v_mfma_f32_32x32x16_bf16 v[48:63], v[144:147], v[64:67], v[48:63]
	ds_read_b128 v[144:147], v187 offset:13920
	v_exp_f32_e32 v74, v74
	v_exp_f32_e32 v75, v75
	s_waitcnt lgkmcnt(2)
	v_mfma_f32_32x32x16_bf16 v[32:47], v[148:151], v[64:67], v[32:47]
	v_exp_f32_e32 v76, v76
	v_exp_f32_e32 v77, v77
	v_mfma_f32_32x32x16_bf16 v[238:253], v[116:119], v[140:143], v[238:253]
	v_exp_f32_e32 v78, v78
	v_exp_f32_e32 v79, v79
	v_mfma_f32_32x32x16_bf16 v[222:237], v[120:123], v[140:143], v[222:237]
	v_add_f32_e32 v164, v72, v164
	v_add_f32_e32 v165, v73, v165
	v_add_f32_e32 v164, v74, v164
	v_add_f32_e32 v165, v75, v165
	v_cvt_pk_bf16_f32 v72, v72, v73
	v_cvt_pk_bf16_f32 v73, v74, v75
	v_add_f32_e32 v164, v76, v164
	v_add_f32_e32 v165, v77, v165
	v_add_f32_e32 v164, v78, v164
	v_add_f32_e32 v165, v79, v165
	v_cvt_pk_bf16_f32 v74, v76, v77
	v_cvt_pk_bf16_f32 v75, v78, v79
	v_cndmask_b32_e64 v72, v72, 0, s[72:73]
	v_cndmask_b32_e64 v73, v73, 0, s[72:73]
	v_cndmask_b32_e64 v74, v74, 0, s[72:73]
	v_cndmask_b32_e64 v75, v75, 0, s[72:73]
	s_nop 1
	s_waitcnt lgkmcnt(1)
	v_mfma_f32_32x32x16_bf16 v[48:63], v[124:127], v[72:75], v[48:63]
	s_waitcnt lgkmcnt(0)
	v_mfma_f32_32x32x16_bf16 v[32:47], v[144:147], v[72:75], v[32:47]
	v_add_f32_e32 v164, v164, v165
	v_cndmask_b32_e64 v164, v164, 0, s[72:73]
	v_add_f32_e32 v106, v106, v164
	v_cmp_lt_f32_e32 vcc, 0x43800000, v164
	s_cbranch_vccz .Lsel_noresc_0b
	s_nop 15
	s_nop 15
	v_mov_b32_e32 v107, v164
	s_nop 1
	v_permlane32_swap_b32_e32 v164, v107
	v_add_f32_e32 v164, v164, v107
	v_log_f32_e32 v160, v164
	s_nop 0
	v_max_f32_e32 v160, 0, v160
	v_exp_f32_e64 v162, -v160
	v_sub_f32_e32 v2, v2, v160
	v_sub_f32_e32 v3, v3, v160
	v_sub_f32_e32 v4, v4, v160
	v_sub_f32_e32 v5, v5, v160
	v_sub_f32_e32 v6, v6, v160
	v_sub_f32_e32 v7, v7, v160
	v_sub_f32_e32 v8, v8, v160
	v_sub_f32_e32 v9, v9, v160
	v_sub_f32_e32 v10, v10, v160
	v_sub_f32_e32 v11, v11, v160
	v_sub_f32_e32 v12, v12, v160
	v_sub_f32_e32 v13, v13, v160
	v_sub_f32_e32 v14, v14, v160
	v_sub_f32_e32 v15, v15, v160
	v_sub_f32_e32 v16, v16, v160
	v_sub_f32_e32 v17, v17, v160
	v_mul_f32_e32 v106, v106, v162
	v_pk_mul_f32 v[48:49], v[48:49], v[162:163] op_sel_hi:[1,0]
	v_pk_mul_f32 v[32:33], v[32:33], v[162:163] op_sel_hi:[1,0]
	v_pk_mul_f32 v[50:51], v[50:51], v[162:163] op_sel_hi:[1,0]
	v_pk_mul_f32 v[34:35], v[34:35], v[162:163] op_sel_hi:[1,0]
	v_pk_mul_f32 v[52:53], v[52:53], v[162:163] op_sel_hi:[1,0]
	v_pk_mul_f32 v[36:37], v[36:37], v[162:163] op_sel_hi:[1,0]
	v_pk_mul_f32 v[54:55], v[54:55], v[162:163] op_sel_hi:[1,0]
	v_pk_mul_f32 v[38:39], v[38:39], v[162:163] op_sel_hi:[1,0]
	v_pk_mul_f32 v[56:57], v[56:57], v[162:163] op_sel_hi:[1,0]
	v_pk_mul_f32 v[40:41], v[40:41], v[162:163] op_sel_hi:[1,0]
	v_pk_mul_f32 v[58:59], v[58:59], v[162:163] op_sel_hi:[1,0]
	v_pk_mul_f32 v[42:43], v[42:43], v[162:163] op_sel_hi:[1,0]
	v_pk_mul_f32 v[60:61], v[60:61], v[162:163] op_sel_hi:[1,0]
	v_pk_mul_f32 v[44:45], v[44:45], v[162:163] op_sel_hi:[1,0]
	v_pk_mul_f32 v[62:63], v[62:63], v[162:163] op_sel_hi:[1,0]
	v_pk_mul_f32 v[46:47], v[46:47], v[162:163] op_sel_hi:[1,0]
	v_pk_add_f32 v[238:239], v[238:239], v[160:161] op_sel_hi:[1,0] neg_lo:[0,1] neg_hi:[0,1]
	v_pk_add_f32 v[222:223], v[222:223], v[160:161] op_sel_hi:[1,0] neg_lo:[0,1] neg_hi:[0,1]
	v_pk_add_f32 v[240:241], v[240:241], v[160:161] op_sel_hi:[1,0] neg_lo:[0,1] neg_hi:[0,1]
	v_pk_add_f32 v[224:225], v[224:225], v[160:161] op_sel_hi:[1,0] neg_lo:[0,1] neg_hi:[0,1]
	v_pk_add_f32 v[242:243], v[242:243], v[160:161] op_sel_hi:[1,0] neg_lo:[0,1] neg_hi:[0,1]
	v_pk_add_f32 v[226:227], v[226:227], v[160:161] op_sel_hi:[1,0] neg_lo:[0,1] neg_hi:[0,1]
	v_pk_add_f32 v[244:245], v[244:245], v[160:161] op_sel_hi:[1,0] neg_lo:[0,1] neg_hi:[0,1]
	v_pk_add_f32 v[228:229], v[228:229], v[160:161] op_sel_hi:[1,0] neg_lo:[0,1] neg_hi:[0,1]
	v_pk_add_f32 v[246:247], v[246:247], v[160:161] op_sel_hi:[1,0] neg_lo:[0,1] neg_hi:[0,1]
	v_pk_add_f32 v[230:231], v[230:231], v[160:161] op_sel_hi:[1,0] neg_lo:[0,1] neg_hi:[0,1]
	v_pk_add_f32 v[248:249], v[248:249], v[160:161] op_sel_hi:[1,0] neg_lo:[0,1] neg_hi:[0,1]
	v_pk_add_f32 v[232:233], v[232:233], v[160:161] op_sel_hi:[1,0] neg_lo:[0,1] neg_hi:[0,1]
	v_pk_add_f32 v[250:251], v[250:251], v[160:161] op_sel_hi:[1,0] neg_lo:[0,1] neg_hi:[0,1]
	v_pk_add_f32 v[234:235], v[234:235], v[160:161] op_sel_hi:[1,0] neg_lo:[0,1] neg_hi:[0,1]
	v_pk_add_f32 v[252:253], v[252:253], v[160:161] op_sel_hi:[1,0] neg_lo:[0,1] neg_hi:[0,1]
	v_pk_add_f32 v[236:237], v[236:237], v[160:161] op_sel_hi:[1,0] neg_lo:[0,1] neg_hi:[0,1]
	s_nop 1

.Lsel_nodiag_1b:
	v_add_u32_e32 v187, s81, v208
	ds_read_b128 v[124:127], v187 offset:9216
	ds_read_b128 v[144:147], v187 offset:13824
	ds_read_b128 v[148:151], v187 offset:9248
	s_waitcnt lgkmcnt(6)
	v_mfma_f32_32x32x16_bf16 v[80:95], v[108:111], v[128:131], v[2:17]
	ds_read_b128 v[108:111], v0 offset:64
	s_waitcnt lgkmcnt(6)
	v_mfma_f32_32x32x16_bf16 v[64:79], v[112:115], v[128:131], v[2:17]
	ds_read_b128 v[112:115], v0 offset:4672
	v_exp_f32_e32 v238, v238
	v_exp_f32_e32 v239, v239
	v_exp_f32_e32 v240, v240
	v_exp_f32_e32 v241, v241
	v_exp_f32_e32 v242, v242
	v_exp_f32_e32 v243, v243
	v_exp_f32_e32 v244, v244
	v_exp_f32_e32 v245, v245
	v_add_f32_e32 v164, 0, v238
	v_add_f32_e32 v165, 0, v239
	v_add_f32_e32 v164, v240, v164
	v_add_f32_e32 v165, v241, v165
	v_cvt_pk_bf16_f32 v238, v238, v239
	v_cvt_pk_bf16_f32 v239, v240, v241
	v_add_f32_e32 v164, v242, v164
	v_add_f32_e32 v165, v243, v165
	v_add_f32_e32 v164, v244, v164
	v_add_f32_e32 v165, v245, v165
	v_cvt_pk_bf16_f32 v240, v242, v243
	v_cvt_pk_bf16_f32 v241, v244, v245
	v_cndmask_b32_e64 v238, v238, 0, s[72:73]
	v_cndmask_b32_e64 v239, v239, 0, s[72:73]
	v_cndmask_b32_e64 v240, v240, 0, s[72:73]
	v_cndmask_b32_e64 v241, v241, 0, s[72:73]
	v_exp_f32_e32 v246, v246
	v_exp_f32_e32 v247, v247
	s_waitcnt lgkmcnt(4)
	v_mfma_f32_32x32x16_bf16 v[48:63], v[124:127], v[238:241], v[48:63]
	ds_read_b128 v[124:127], v187 offset:13856
	v_exp_f32_e32 v248, v248
	v_exp_f32_e32 v249, v249
	s_waitcnt lgkmcnt(4)
	v_mfma_f32_32x32x16_bf16 v[32:47], v[144:147], v[238:241], v[32:47]
	ds_read_b128 v[144:147], v187 offset:9280
	v_exp_f32_e32 v250, v250
	v_exp_f32_e32 v251, v251
	v_mfma_f32_32x32x16_bf16 v[80:95], v[116:119], v[132:135], v[80:95]
	ds_read_b128 v[116:119], v0 offset:96
	v_exp_f32_e32 v252, v252
	v_exp_f32_e32 v253, v253
	v_mfma_f32_32x32x16_bf16 v[64:79], v[120:123], v[132:135], v[64:79]
	ds_read_b128 v[120:123], v0 offset:4704
	v_add_f32_e32 v164, v246, v164
	v_add_f32_e32 v165, v247, v165
	v_add_f32_e32 v164, v248, v164
	v_add_f32_e32 v165, v249, v165
	v_cvt_pk_bf16_f32 v246, v246, v247
	v_cvt_pk_bf16_f32 v247, v248, v249
	v_add_f32_e32 v164, v250, v164
	v_add_f32_e32 v165, v251, v165
	v_add_f32_e32 v164, v252, v164
	v_add_f32_e32 v165, v253, v165
	v_cvt_pk_bf16_f32 v248, v250, v251
	v_cvt_pk_bf16_f32 v249, v252, v253
	v_cndmask_b32_e64 v246, v246, 0, s[72:73]
	v_cndmask_b32_e64 v247, v247, 0, s[72:73]
	v_cndmask_b32_e64 v248, v248, 0, s[72:73]
	v_cndmask_b32_e64 v249, v249, 0, s[72:73]
	v_exp_f32_e32 v222, v222
	v_exp_f32_e32 v223, v223
	s_waitcnt lgkmcnt(6)
	v_mfma_f32_32x32x16_bf16 v[48:63], v[148:151], v[246:249], v[48:63]
	ds_read_b128 v[148:151], v187 offset:13888
	v_exp_f32_e32 v224, v224
	v_exp_f32_e32 v225, v225
	s_waitcnt lgkmcnt(4)
	v_mfma_f32_32x32x16_bf16 v[32:47], v[124:127], v[246:249], v[32:47]
	ds_read_b128 v[124:127], v187 offset:9312
	v_exp_f32_e32 v226, v226
	v_exp_f32_e32 v227, v227
	v_mfma_f32_32x32x16_bf16 v[80:95], v[108:111], v[136:139], v[80:95]
	v_exp_f32_e32 v228, v228
	v_exp_f32_e32 v229, v229
	v_mfma_f32_32x32x16_bf16 v[64:79], v[112:115], v[136:139], v[64:79]
	v_add_f32_e32 v164, v222, v164
	v_add_f32_e32 v165, v223, v165
	v_add_f32_e32 v164, v224, v164
	v_add_f32_e32 v165, v225, v165
	v_cvt_pk_bf16_f32 v222, v222, v223
	v_cvt_pk_bf16_f32 v223, v224, v225
	v_add_f32_e32 v164, v226, v164
	v_add_f32_e32 v165, v227, v165
	v_add_f32_e32 v164, v228, v164
	v_add_f32_e32 v165, v229, v165
	v_cvt_pk_bf16_f32 v224, v226, v227
	v_cvt_pk_bf16_f32 v225, v228, v229
	v_cndmask_b32_e64 v222, v222, 0, s[72:73]
	v_cndmask_b32_e64 v223, v223, 0, s[72:73]
	v_cndmask_b32_e64 v224, v224, 0, s[72:73]
	v_cndmask_b32_e64 v225, v225, 0, s[72:73]
	v_exp_f32_e32 v230, v230
	v_exp_f32_e32 v231, v231
	s_waitcnt lgkmcnt(4)
	v_mfma_f32_32x32x16_bf16 v[48:63], v[144:147], v[222:225], v[48:63]
	ds_read_b128 v[144:147], v187 offset:13920
	v_exp_f32_e32 v232, v232
	v_exp_f32_e32 v233, v233
	s_waitcnt lgkmcnt(2)
	v_mfma_f32_32x32x16_bf16 v[32:47], v[148:151], v[222:225], v[32:47]
	v_exp_f32_e32 v234, v234
	v_exp_f32_e32 v235, v235
	v_mfma_f32_32x32x16_bf16 v[80:95], v[116:119], v[140:143], v[80:95]
	v_exp_f32_e32 v236, v236
	v_exp_f32_e32 v237, v237
	v_mfma_f32_32x32x16_bf16 v[64:79], v[120:123], v[140:143], v[64:79]
	v_add_f32_e32 v164, v230, v164
	v_add_f32_e32 v165, v231, v165
	v_add_f32_e32 v164, v232, v164
	v_add_f32_e32 v165, v233, v165
	v_cvt_pk_bf16_f32 v230, v230, v231
	v_cvt_pk_bf16_f32 v231, v232, v233
	v_add_f32_e32 v164, v234, v164
	v_add_f32_e32 v165, v235, v165
	v_add_f32_e32 v164, v236, v164
	v_add_f32_e32 v165, v237, v165
	v_cvt_pk_bf16_f32 v232, v234, v235
	v_cvt_pk_bf16_f32 v233, v236, v237
	v_cndmask_b32_e64 v230, v230, 0, s[72:73]
	v_cndmask_b32_e64 v231, v231, 0, s[72:73]
	v_cndmask_b32_e64 v232, v232, 0, s[72:73]
	v_cndmask_b32_e64 v233, v233, 0, s[72:73]
	s_nop 1
	s_waitcnt lgkmcnt(1)
	v_mfma_f32_32x32x16_bf16 v[48:63], v[124:127], v[230:233], v[48:63]
	s_waitcnt lgkmcnt(0)
	v_mfma_f32_32x32x16_bf16 v[32:47], v[144:147], v[230:233], v[32:47]
	v_add_f32_e32 v164, v164, v165
	v_cndmask_b32_e64 v164, v164, 0, s[72:73]
	v_add_f32_e32 v106, v106, v164
	v_cmp_lt_f32_e32 vcc, 0x43800000, v164
	s_cbranch_vccz .Lsel_noresc_1b
	s_nop 15
	s_nop 15
	v_mov_b32_e32 v107, v164
	s_nop 1
	v_permlane32_swap_b32_e32 v164, v107
	v_add_f32_e32 v164, v164, v107
	v_log_f32_e32 v160, v164
	s_nop 0
	v_max_f32_e32 v160, 0, v160
	v_exp_f32_e64 v162, -v160
	v_sub_f32_e32 v2, v2, v160
	v_sub_f32_e32 v3, v3, v160
	v_sub_f32_e32 v4, v4, v160
	v_sub_f32_e32 v5, v5, v160
	v_sub_f32_e32 v6, v6, v160
	v_sub_f32_e32 v7, v7, v160
	v_sub_f32_e32 v8, v8, v160
	v_sub_f32_e32 v9, v9, v160
	v_sub_f32_e32 v10, v10, v160
	v_sub_f32_e32 v11, v11, v160
	v_sub_f32_e32 v12, v12, v160
	v_sub_f32_e32 v13, v13, v160
	v_sub_f32_e32 v14, v14, v160
	v_sub_f32_e32 v15, v15, v160
	v_sub_f32_e32 v16, v16, v160
	v_sub_f32_e32 v17, v17, v160
	v_mul_f32_e32 v106, v106, v162
	v_pk_mul_f32 v[48:49], v[48:49], v[162:163] op_sel_hi:[1,0]
	v_pk_mul_f32 v[32:33], v[32:33], v[162:163] op_sel_hi:[1,0]
	v_pk_mul_f32 v[50:51], v[50:51], v[162:163] op_sel_hi:[1,0]
	v_pk_mul_f32 v[34:35], v[34:35], v[162:163] op_sel_hi:[1,0]
	v_pk_mul_f32 v[52:53], v[52:53], v[162:163] op_sel_hi:[1,0]
	v_pk_mul_f32 v[36:37], v[36:37], v[162:163] op_sel_hi:[1,0]
	v_pk_mul_f32 v[54:55], v[54:55], v[162:163] op_sel_hi:[1,0]
	v_pk_mul_f32 v[38:39], v[38:39], v[162:163] op_sel_hi:[1,0]
	v_pk_mul_f32 v[56:57], v[56:57], v[162:163] op_sel_hi:[1,0]
	v_pk_mul_f32 v[40:41], v[40:41], v[162:163] op_sel_hi:[1,0]
	v_pk_mul_f32 v[58:59], v[58:59], v[162:163] op_sel_hi:[1,0]
	v_pk_mul_f32 v[42:43], v[42:43], v[162:163] op_sel_hi:[1,0]
	v_pk_mul_f32 v[60:61], v[60:61], v[162:163] op_sel_hi:[1,0]
	v_pk_mul_f32 v[44:45], v[44:45], v[162:163] op_sel_hi:[1,0]
	v_pk_mul_f32 v[62:63], v[62:63], v[162:163] op_sel_hi:[1,0]
	v_pk_mul_f32 v[46:47], v[46:47], v[162:163] op_sel_hi:[1,0]
	v_pk_add_f32 v[80:81], v[80:81], v[160:161] op_sel_hi:[1,0] neg_lo:[0,1] neg_hi:[0,1]
	v_pk_add_f32 v[64:65], v[64:65], v[160:161] op_sel_hi:[1,0] neg_lo:[0,1] neg_hi:[0,1]
	v_pk_add_f32 v[82:83], v[82:83], v[160:161] op_sel_hi:[1,0] neg_lo:[0,1] neg_hi:[0,1]
	v_pk_add_f32 v[66:67], v[66:67], v[160:161] op_sel_hi:[1,0] neg_lo:[0,1] neg_hi:[0,1]
	v_pk_add_f32 v[84:85], v[84:85], v[160:161] op_sel_hi:[1,0] neg_lo:[0,1] neg_hi:[0,1]
	v_pk_add_f32 v[68:69], v[68:69], v[160:161] op_sel_hi:[1,0] neg_lo:[0,1] neg_hi:[0,1]
	v_pk_add_f32 v[86:87], v[86:87], v[160:161] op_sel_hi:[1,0] neg_lo:[0,1] neg_hi:[0,1]
	v_pk_add_f32 v[70:71], v[70:71], v[160:161] op_sel_hi:[1,0] neg_lo:[0,1] neg_hi:[0,1]
	v_pk_add_f32 v[88:89], v[88:89], v[160:161] op_sel_hi:[1,0] neg_lo:[0,1] neg_hi:[0,1]
	v_pk_add_f32 v[72:73], v[72:73], v[160:161] op_sel_hi:[1,0] neg_lo:[0,1] neg_hi:[0,1]
	v_pk_add_f32 v[90:91], v[90:91], v[160:161] op_sel_hi:[1,0] neg_lo:[0,1] neg_hi:[0,1]
	v_pk_add_f32 v[74:75], v[74:75], v[160:161] op_sel_hi:[1,0] neg_lo:[0,1] neg_hi:[0,1]
	v_pk_add_f32 v[92:93], v[92:93], v[160:161] op_sel_hi:[1,0] neg_lo:[0,1] neg_hi:[0,1]
	v_pk_add_f32 v[76:77], v[76:77], v[160:161] op_sel_hi:[1,0] neg_lo:[0,1] neg_hi:[0,1]
	v_pk_add_f32 v[94:95], v[94:95], v[160:161] op_sel_hi:[1,0] neg_lo:[0,1] neg_hi:[0,1]
	v_pk_add_f32 v[78:79], v[78:79], v[160:161] op_sel_hi:[1,0] neg_lo:[0,1] neg_hi:[0,1]
	s_nop 1
